# barrier latency trimming: arrival atomic issued before the LDS reads and the L2 invalidate, poll loop without sleep (barriers 2-5)
# speedup vs baseline: 1.0069x; 1.0045x over previous
; __device__ __forceinline__ unsigned xb_add(unsigned* p, unsigned v) { return __hip_atomic_fetch_add(p, v, __ATOMIC_RELAXED, __HIP_MEMORY_SCOPE_AGENT); }
; __device__ __forceinline__ XbState xcd_barrier_arrive(const XcdBarrier& b) {
;     asm volatile("s_waitcnt vmcnt(0)" ::: "memory");
;     __syncthreads();
;     unsigned* bar = b.bar;
;     XbState st; st.gen = 0u; st.tg = 0u; st.lastx = false; st.lastt = false;
;     if (threadIdx.x == 0) {
;         __builtin_amdgcn_s_waitcnt(0);
;         unsigned nloc = b.st[0], nx = b.st[1];
;         if (nloc == 0u) { xcd_barrier_complete(bar, b.x, nloc, nx); b.st[0] = nloc; b.st[1] = nx; }
;         const unsigned old = xb_add(&bar[XB_XSUB(b.x)], 1u);
;         st.gen = old / nloc; st.lastx = (old + 1u == (st.gen + 1u) * nloc);
;         if (st.lastx) {
;             __builtin_amdgcn_fence(__ATOMIC_RELEASE, "agent");
;             asm volatile("s_waitcnt vmcnt(0)" ::: "memory");
;             const unsigned og = xb_add(&bar[XB_TOP], 1u);
.Lside_done:
	s_waitcnt vmcnt(0)
	v_mov_b32_e32 v3, 0
	s_mov_b64 s[8:9], 0
	s_waitcnt lgkmcnt(0)
	s_mov_b64 s[6:7], 0
	v_mov_b32_e32 v2, 0
	s_waitcnt vmcnt(0)
	s_barrier
	s_and_saveexec_b64 s[4:5], s[14:15]
	s_cbranch_execz .LBB0_382
	s_waitcnt vmcnt(0) lgkmcnt(0)
	s_lshl_b32 s8, s33, 8
	s_add_u32 s8, s82, s8
	s_addc_u32 s9, s83, 0
	v_mov_b32_e32 v7, 0x1000
	v_mov_b32_e32 v5, 1
	global_atomic_add v6, v7, v5, s[8:9] offset:1024 sc0
	v_mov_b32_e32 v1, 0x27c20
	ds_read_b32 v3, v1
	ds_read_b32 v4, v1 offset:4
	buffer_inv sc1
	s_waitcnt vmcnt(0) lgkmcnt(0)
	v_add_u32_e32 v6, 1, v6
	v_mul_u32_u24_e32 v7, 2, v3
	v_mul_u32_u24_e32 v2, 2, v4
	v_cmp_eq_u32_e32 vcc, v6, v7
	s_and_saveexec_b64 s[8:9], vcc
	s_cbranch_execz .Lbar2_notlast
	buffer_wbl2 sc1
	s_waitcnt vmcnt(0)
	v_mov_b32_e32 v1, 0x7000
	global_atomic_add v1, v5, s[30:31] offset:1024

; __device__ __forceinline__ unsigned xb_ld(unsigned* p)              { return __hip_atomic_load(p, __ATOMIC_RELAXED, __HIP_MEMORY_SCOPE_AGENT); }
; #define XB_SPIN(cond, bar) do { unsigned _sp = 0; while (cond) { __builtin_amdgcn_s_sleep(1); \
;     if ((++_sp & 255u) == 0u) { if (xb_ld(&(bar)[XB_TMO])) break; if (_sp > XB_SPIN_CAP) { atomicAdd(&(bar)[XB_TMO], 1u); break; } } } } while (0)
; __device__ __forceinline__ void xcd_barrier_wait(const XcdBarrier& b, const XbState& st) {
;     unsigned* bar = b.bar;
;     if (threadIdx.x == 0) {
;         if (st.lastx) {
;             if (!st.lastt) XB_SPIN(xb_ld(&bar[XB_TOPGEN]) == st.tg, bar);
;             __builtin_amdgcn_fence(__ATOMIC_ACQUIRE, "agent");
;             asm volatile("s_waitcnt vmcnt(0)" ::: "memory");
;         } else {
;             XB_SPIN(xb_ld(&bar[XB_TOPGEN]) == st.gen, bar);
;             __builtin_amdgcn_fence(__ATOMIC_ACQUIRE, "agent");
;             asm volatile("s_waitcnt vmcnt(0)" ::: "memory");
;         }
.Lbar2_poll:
	global_load_dword v3, v1, s[30:31] offset:1024 sc1
	s_waitcnt vmcnt(0)
	v_cmp_ge_u32_e32 vcc, v3, v2
	s_cbranch_vccnz .Lbar2_go
	s_nop 0
	s_add_u32 s16, s16, 1
	s_cmp_lt_u32 s16, 0x8000
	s_cbranch_scc1 .Lbar2_poll

; __device__ __forceinline__ unsigned xb_add(unsigned* p, unsigned v) { return __hip_atomic_fetch_add(p, v, __ATOMIC_RELAXED, __HIP_MEMORY_SCOPE_AGENT); }
; __device__ __forceinline__ XbState xcd_barrier_arrive(const XcdBarrier& b) {
;     asm volatile("s_waitcnt vmcnt(0)" ::: "memory");
;     __syncthreads();
;     unsigned* bar = b.bar;
;     XbState st; st.gen = 0u; st.tg = 0u; st.lastx = false; st.lastt = false;
;     if (threadIdx.x == 0) {
;         __builtin_amdgcn_s_waitcnt(0);
;         unsigned nloc = b.st[0], nx = b.st[1];
;         if (nloc == 0u) { xcd_barrier_complete(bar, b.x, nloc, nx); b.st[0] = nloc; b.st[1] = nx; }
;         const unsigned old = xb_add(&bar[XB_XSUB(b.x)], 1u);
;         st.gen = old / nloc; st.lastx = (old + 1u == (st.gen + 1u) * nloc);
;         if (st.lastx) {
;             __builtin_amdgcn_fence(__ATOMIC_RELEASE, "agent");
;             asm volatile("s_waitcnt vmcnt(0)" ::: "memory");
;             const unsigned og = xb_add(&bar[XB_TOP], 1u);
;             st.tg = og / nx; st.lastt = (og + 1u == (st.tg + 1u) * nx);
;             if (st.lastt) xb_add(&bar[XB_TOPGEN], 1u);
.LBB0_565:
	s_waitcnt vmcnt(0)
	v_mov_b32_e32 v3, 0
	s_waitcnt lgkmcnt(0)
	s_mov_b64 s[16:17], 0
	s_mov_b64 s[8:9], 0
	v_mov_b32_e32 v2, 0
	s_barrier
	s_and_saveexec_b64 s[6:7], s[14:15]
	s_cbranch_execz .LBB0_592
	s_waitcnt vmcnt(0) lgkmcnt(0)
	s_lshl_b32 s8, s33, 8
	s_add_u32 s8, s82, s8
	s_addc_u32 s9, s83, 0
	v_mov_b32_e32 v7, 0x1000
	v_mov_b32_e32 v5, 1
	global_atomic_add v6, v7, v5, s[8:9] offset:1024 sc0
	v_mov_b32_e32 v1, 0x27c20
	ds_read_b32 v3, v1
	ds_read_b32 v4, v1 offset:4
	buffer_inv sc1
	s_waitcnt vmcnt(0) lgkmcnt(0)
	v_add_u32_e32 v6, 1, v6
	v_mul_u32_u24_e32 v7, 3, v3
	v_mul_u32_u24_e32 v2, 3, v4
	v_cmp_eq_u32_e32 vcc, v6, v7
	s_and_saveexec_b64 s[8:9], vcc
	s_cbranch_execz .Lbar3_notlast
	buffer_wbl2 sc1
	s_waitcnt vmcnt(0)
	v_mov_b32_e32 v1, 0x7000
	global_atomic_add v1, v5, s[30:31] offset:1024

; __device__ __forceinline__ unsigned xb_add(unsigned* p, unsigned v) { return __hip_atomic_fetch_add(p, v, __ATOMIC_RELAXED, __HIP_MEMORY_SCOPE_AGENT); }
; __device__ __forceinline__ XbState xcd_barrier_arrive(const XcdBarrier& b) {
;     asm volatile("s_waitcnt vmcnt(0)" ::: "memory");
;     __syncthreads();
;     unsigned* bar = b.bar;
;     XbState st; st.gen = 0u; st.tg = 0u; st.lastx = false; st.lastt = false;
;     if (threadIdx.x == 0) {
;         __builtin_amdgcn_s_waitcnt(0);
;         unsigned nloc = b.st[0], nx = b.st[1];
;         if (nloc == 0u) { xcd_barrier_complete(bar, b.x, nloc, nx); b.st[0] = nloc; b.st[1] = nx; }
;         const unsigned old = xb_add(&bar[XB_XSUB(b.x)], 1u);
;         st.gen = old / nloc; st.lastx = (old + 1u == (st.gen + 1u) * nloc);
;         if (st.lastx) {
;             __builtin_amdgcn_fence(__ATOMIC_RELEASE, "agent");
;             asm volatile("s_waitcnt vmcnt(0)" ::: "memory");
;             const unsigned og = xb_add(&bar[XB_TOP], 1u);
;             st.tg = og / nx; st.lastt = (og + 1u == (st.tg + 1u) * nx);
;             if (st.lastt) xb_add(&bar[XB_TOPGEN], 1u);
.LBB0_670:
	s_waitcnt vmcnt(0)
	v_mov_b32_e32 v3, 0
	s_mov_b64 s[16:17], 0
	s_mov_b64 s[8:9], 0
	v_mov_b32_e32 v2, 0
	s_barrier
	s_and_saveexec_b64 s[6:7], s[14:15]
	s_cbranch_execz .LBB0_697
	s_waitcnt vmcnt(0) lgkmcnt(0)
	s_lshl_b32 s8, s33, 8
	s_add_u32 s8, s82, s8
	s_addc_u32 s9, s83, 0
	v_mov_b32_e32 v7, 0x1000
	v_mov_b32_e32 v5, 1
	global_atomic_add v6, v7, v5, s[8:9] offset:1024 sc0
	v_mov_b32_e32 v1, 0x27c20
	ds_read_b32 v3, v1
	ds_read_b32 v4, v1 offset:4
	buffer_inv sc1
	s_waitcnt vmcnt(0) lgkmcnt(0)
	v_add_u32_e32 v6, 1, v6
	v_mul_u32_u24_e32 v7, 4, v3
	v_mul_u32_u24_e32 v2, 4, v4
	v_cmp_eq_u32_e32 vcc, v6, v7
	s_and_saveexec_b64 s[8:9], vcc
	s_cbranch_execz .Lbar4_notlast
	buffer_wbl2 sc1
	s_waitcnt vmcnt(0)
	v_mov_b32_e32 v1, 0x7000
	global_atomic_add v1, v5, s[30:31] offset:1024

; __device__ __forceinline__ unsigned xb_add(unsigned* p, unsigned v) { return __hip_atomic_fetch_add(p, v, __ATOMIC_RELAXED, __HIP_MEMORY_SCOPE_AGENT); }
; __device__ __forceinline__ XbState xcd_barrier_arrive(const XcdBarrier& b) {
;     asm volatile("s_waitcnt vmcnt(0)" ::: "memory");
;     __syncthreads();
;     unsigned* bar = b.bar;
;     XbState st; st.gen = 0u; st.tg = 0u; st.lastx = false; st.lastt = false;
;     if (threadIdx.x == 0) {
;         __builtin_amdgcn_s_waitcnt(0);
;         unsigned nloc = b.st[0], nx = b.st[1];
;         if (nloc == 0u) { xcd_barrier_complete(bar, b.x, nloc, nx); b.st[0] = nloc; b.st[1] = nx; }
;         const unsigned old = xb_add(&bar[XB_XSUB(b.x)], 1u);
;         st.gen = old / nloc; st.lastx = (old + 1u == (st.gen + 1u) * nloc);
;         if (st.lastx) {
;             __builtin_amdgcn_fence(__ATOMIC_RELEASE, "agent");
;             asm volatile("s_waitcnt vmcnt(0)" ::: "memory");
;             const unsigned og = xb_add(&bar[XB_TOP], 1u);
;             st.tg = og / nx; st.lastt = (og + 1u == (st.tg + 1u) * nx);
;             if (st.lastt) xb_add(&bar[XB_TOPGEN], 1u);
.LBB0_772:
	s_waitcnt vmcnt(0)
	v_mov_b32_e32 v67, 0
	s_mov_b64 s[10:11], 0
	s_mov_b64 s[8:9], 0
	v_mov_b32_e32 v66, 0
	s_waitcnt vmcnt(0)
	s_barrier
	s_and_saveexec_b64 s[6:7], s[14:15]
	s_cbranch_execz .LBB0_799
	s_waitcnt vmcnt(0) lgkmcnt(0)
	s_lshl_b32 s8, s33, 8
	s_add_u32 s8, s82, s8
	s_addc_u32 s9, s83, 0
	v_mov_b32_e32 v6, 0x1000
	v_mov_b32_e32 v4, 1
	global_atomic_add v5, v6, v4, s[8:9] offset:1024 sc0
	v_mov_b32_e32 v3, 0x27c20
	ds_read_b32 v1, v3
	ds_read_b32 v2, v3 offset:4
	buffer_inv sc1
	s_waitcnt vmcnt(0) lgkmcnt(0)
	v_add_u32_e32 v5, 1, v5
	v_mul_u32_u24_e32 v6, 5, v1
	v_mul_u32_u24_e32 v66, 5, v2
	v_cmp_eq_u32_e32 vcc, v5, v6
	s_and_saveexec_b64 s[8:9], vcc
	s_cbranch_execz .Lbar5_notlast
	buffer_wbl2 sc1
	s_waitcnt vmcnt(0)
	v_mov_b32_e32 v3, 0x7000
	global_atomic_add v3, v4, s[30:31] offset:1024

; __device__ __forceinline__ unsigned xb_ld(unsigned* p)              { return __hip_atomic_load(p, __ATOMIC_RELAXED, __HIP_MEMORY_SCOPE_AGENT); }
; #define XB_SPIN(cond, bar) do { unsigned _sp = 0; while (cond) { __builtin_amdgcn_s_sleep(1); \
;     if ((++_sp & 255u) == 0u) { if (xb_ld(&(bar)[XB_TMO])) break; if (_sp > XB_SPIN_CAP) { atomicAdd(&(bar)[XB_TMO], 1u); break; } } } } while (0)
; __device__ __forceinline__ void xcd_barrier_wait(const XcdBarrier& b, const XbState& st) {
;     unsigned* bar = b.bar;
;     if (threadIdx.x == 0) {
;         if (st.lastx) {
;             if (!st.lastt) XB_SPIN(xb_ld(&bar[XB_TOPGEN]) == st.tg, bar);
;             __builtin_amdgcn_fence(__ATOMIC_ACQUIRE, "agent");
;             asm volatile("s_waitcnt vmcnt(0)" ::: "memory");
;         } else {
;             XB_SPIN(xb_ld(&bar[XB_TOPGEN]) == st.gen, bar);
;             __builtin_amdgcn_fence(__ATOMIC_ACQUIRE, "agent");
;             asm volatile("s_waitcnt vmcnt(0)" ::: "memory");
;         }
.Lbar5_poll:
	global_load_dword v67, v1, s[30:31] offset:1024 sc1
	s_waitcnt vmcnt(0)
	v_cmp_ge_u32_e32 vcc, v67, v66
	s_cbranch_vccnz .Lbar5_go
	s_nop 0
	s_add_u32 s16, s16, 1
	s_cmp_lt_u32 s16, 0x8000
	s_cbranch_scc1 .Lbar5_poll
